# out-proj epilogue: residual loads issued 16 deep with counted vmcnt instead of load-wait-store ladder
# speedup vs baseline: 1.0210x; 1.0103x over previous
;     __device__ __forceinline__ void operator()(const pg8::f32x4 (&acc)[2][2][4][2], const pg8::Unit& u, int wr, int wc, int fr, int fq) const {
; #pragma unroll
;         for (int ai = 0; ai < 2; ++ai)
; #pragma unroll
;             for (int m = 0; m < 4; ++m) {
;                 const size_t row = (size_t)u.pm * 256 + 128 * ai + 64 * wr + 16 * m + fr;
; #pragma unroll
;                 for (int bj = 0; bj < 2; ++bj)
; #pragma unroll
;                     for (int n = 0; n < 2; ++n) {
;                         const size_t off = row * DM + u.pn * 256 + 128 * bj + 32 * wc + 16 * n + 4 * fq;
;                         const f32x4 r = *(const f32x4*)(src + off);
;                         *(f32x4*)(out + off) = r + acc[ai][bj][m][n];
;                     }
;                 asm volatile("" ::: "memory");
;             }
.LBB0_521:
	s_ashr_i32 s3, s2, 31
	s_lshl_b32 s15, s44, 8
	s_ashr_i32 s17, s15, 31
	s_lshl_b64 s[2:3], s[2:3], 19
	v_mov_b32_e32 v141, s17
	v_or_b32_e32 v140, s15, v132
	v_lshl_add_u64 v[142:143], s[2:3], 0, v[134:135]
	v_lshl_add_u64 v[140:141], v[142:143], 0, v[140:141]
	v_lshlrev_b64 v[140:141], 2, v[140:141]
	v_lshl_add_u64 v[142:143], s[0:1], 0, v[140:141]
	v_lshl_add_u64 v[154:155], s[12:13], 0, v[140:141]
	global_load_dwordx4 v[196:199], v[142:143], off
	global_load_dwordx4 v[200:203], v[142:143], off offset:64
	global_load_dwordx4 v[204:207], v[142:143], off offset:512
	global_load_dwordx4 v[208:211], v[142:143], off offset:576
	s_mov_b64 s[2:3], 0x20000
	v_lshl_add_u64 v[156:157], v[142:143], 0, s[2:3]
	global_load_dwordx4 v[212:215], v[156:157], off
	global_load_dwordx4 v[216:219], v[156:157], off offset:64
	global_load_dwordx4 v[220:223], v[156:157], off offset:512
	global_load_dwordx4 v[224:227], v[156:157], off offset:576
	s_mov_b64 s[2:3], 0x40000
	v_lshl_add_u64 v[156:157], v[142:143], 0, s[2:3]
	global_load_dwordx4 v[228:231], v[156:157], off
	global_load_dwordx4 v[232:235], v[156:157], off offset:64
	global_load_dwordx4 v[236:239], v[156:157], off offset:512
	global_load_dwordx4 v[240:243], v[156:157], off offset:576
	s_mov_b64 s[2:3], 0x60000
	v_lshl_add_u64 v[156:157], v[142:143], 0, s[2:3]
	global_load_dwordx4 v[244:247], v[156:157], off
	global_load_dwordx4 v[248:251], v[156:157], off offset:64
	global_load_dwordx4 v[146:149], v[156:157], off offset:512
	global_load_dwordx4 v[150:153], v[156:157], off offset:576
	s_mov_b64 s[2:3], 0x100000
	v_lshl_add_u64 v[156:157], v[142:143], 0, s[2:3]
	s_waitcnt vmcnt(15)
	v_pk_add_f32 v[126:127], v[126:127], v[196:197]
	v_pk_add_f32 v[128:129], v[128:129], v[198:199]
	global_store_dwordx4 v[154:155], v[126:129], off
	global_load_dwordx4 v[196:199], v[156:157], off
	s_waitcnt vmcnt(16)
	v_pk_add_f32 v[122:123], v[122:123], v[200:201]
	v_pk_add_f32 v[124:125], v[124:125], v[202:203]
	global_store_dwordx4 v[154:155], v[122:125], off offset:64
	global_load_dwordx4 v[200:203], v[156:157], off offset:64
	s_waitcnt vmcnt(17)
	v_pk_add_f32 v[118:119], v[118:119], v[204:205]
	v_pk_add_f32 v[120:121], v[120:121], v[206:207]
	global_store_dwordx4 v[154:155], v[118:121], off offset:512
	global_load_dwordx4 v[204:207], v[156:157], off offset:512
	s_waitcnt vmcnt(18)
	v_pk_add_f32 v[114:115], v[114:115], v[208:209]
	v_pk_add_f32 v[116:117], v[116:117], v[210:211]
	global_store_dwordx4 v[154:155], v[114:117], off offset:576
	global_load_dwordx4 v[208:211], v[156:157], off offset:576
	s_mov_b64 s[2:3], 0x20000
	v_lshl_add_u64 v[158:159], v[154:155], 0, s[2:3]
	s_mov_b64 s[2:3], 0x120000
	v_lshl_add_u64 v[156:157], v[142:143], 0, s[2:3]
	s_waitcnt vmcnt(19)
	v_pk_add_f32 v[110:111], v[110:111], v[212:213]
	v_pk_add_f32 v[112:113], v[112:113], v[214:215]
	global_store_dwordx4 v[158:159], v[110:113], off
	global_load_dwordx4 v[212:215], v[156:157], off
	s_waitcnt vmcnt(20)
	v_pk_add_f32 v[106:107], v[106:107], v[216:217]
	v_pk_add_f32 v[108:109], v[108:109], v[218:219]
	global_store_dwordx4 v[158:159], v[106:109], off offset:64
	global_load_dwordx4 v[216:219], v[156:157], off offset:64
	s_waitcnt vmcnt(21)
	v_pk_add_f32 v[102:103], v[102:103], v[220:221]
	v_pk_add_f32 v[104:105], v[104:105], v[222:223]
	global_store_dwordx4 v[158:159], v[102:105], off offset:512
	global_load_dwordx4 v[220:223], v[156:157], off offset:512
	s_waitcnt vmcnt(22)
	v_pk_add_f32 v[98:99], v[98:99], v[224:225]
	v_pk_add_f32 v[100:101], v[100:101], v[226:227]
	global_store_dwordx4 v[158:159], v[98:101], off offset:576
	global_load_dwordx4 v[224:227], v[156:157], off offset:576
	s_mov_b64 s[2:3], 0x40000
	v_lshl_add_u64 v[158:159], v[154:155], 0, s[2:3]
	s_mov_b64 s[2:3], 0x140000
	v_lshl_add_u64 v[156:157], v[142:143], 0, s[2:3]
	s_waitcnt vmcnt(23)
	v_pk_add_f32 v[94:95], v[94:95], v[228:229]
	v_pk_add_f32 v[96:97], v[96:97], v[230:231]
	global_store_dwordx4 v[158:159], v[94:97], off
	global_load_dwordx4 v[228:231], v[156:157], off
	s_waitcnt vmcnt(24)
	v_pk_add_f32 v[90:91], v[90:91], v[232:233]
	v_pk_add_f32 v[92:93], v[92:93], v[234:235]
	global_store_dwordx4 v[158:159], v[90:93], off offset:64
	global_load_dwordx4 v[232:235], v[156:157], off offset:64
	s_waitcnt vmcnt(25)
	v_pk_add_f32 v[86:87], v[86:87], v[236:237]
	v_pk_add_f32 v[88:89], v[88:89], v[238:239]
	global_store_dwordx4 v[158:159], v[86:89], off offset:512
	global_load_dwordx4 v[236:239], v[156:157], off offset:512
	s_waitcnt vmcnt(26)
;     __device__ __forceinline__ void operator()(const pg8::f32x4 (&acc)[2][2][4][2], const pg8::Unit& u, int wr, int wc, int fr, int fq) const {
; #pragma unroll
;         for (int ai = 0; ai < 2; ++ai)
; #pragma unroll
;             for (int m = 0; m < 4; ++m) {
;                 const size_t row = (size_t)u.pm * 256 + 128 * ai + 64 * wr + 16 * m + fr;
; #pragma unroll
;                 for (int bj = 0; bj < 2; ++bj)
; #pragma unroll
;                     for (int n = 0; n < 2; ++n) {
;                         const size_t off = row * DM + u.pn * 256 + 128 * bj + 32 * wc + 16 * n + 4 * fq;
;                         const f32x4 r = *(const f32x4*)(src + off);
;                         *(f32x4*)(out + off) = r + acc[ai][bj][m][n];
;                     }
;                 asm volatile("" ::: "memory");
;             }
	v_pk_add_f32 v[82:83], v[82:83], v[240:241]
	v_pk_add_f32 v[84:85], v[84:85], v[242:243]
	global_store_dwordx4 v[158:159], v[82:85], off offset:576
	global_load_dwordx4 v[240:243], v[156:157], off offset:576
	s_mov_b64 s[2:3], 0x60000
	v_lshl_add_u64 v[158:159], v[154:155], 0, s[2:3]
	s_mov_b64 s[2:3], 0x160000
	v_lshl_add_u64 v[156:157], v[142:143], 0, s[2:3]
	s_waitcnt vmcnt(27)
	v_pk_add_f32 v[78:79], v[78:79], v[244:245]
	v_pk_add_f32 v[80:81], v[80:81], v[246:247]
	global_store_dwordx4 v[158:159], v[78:81], off
	global_load_dwordx4 v[244:247], v[156:157], off
	s_waitcnt vmcnt(28)
	v_pk_add_f32 v[74:75], v[74:75], v[248:249]
	v_pk_add_f32 v[76:77], v[76:77], v[250:251]
	global_store_dwordx4 v[158:159], v[74:77], off offset:64
	global_load_dwordx4 v[248:251], v[156:157], off offset:64
	s_waitcnt vmcnt(29)
	v_pk_add_f32 v[70:71], v[70:71], v[146:147]
	v_pk_add_f32 v[72:73], v[72:73], v[148:149]
	global_store_dwordx4 v[158:159], v[70:73], off offset:512
	global_load_dwordx4 v[146:149], v[156:157], off offset:512
	s_waitcnt vmcnt(30)
	v_pk_add_f32 v[66:67], v[66:67], v[150:151]
	v_pk_add_f32 v[68:69], v[68:69], v[152:153]
	global_store_dwordx4 v[158:159], v[66:69], off offset:576
	global_load_dwordx4 v[150:153], v[156:157], off offset:576
	s_mov_b64 s[2:3], 0x100000
	v_lshl_add_u64 v[158:159], v[154:155], 0, s[2:3]
	s_waitcnt vmcnt(30)
	v_pk_add_f32 v[62:63], v[62:63], v[196:197]
	v_pk_add_f32 v[64:65], v[64:65], v[198:199]
	global_store_dwordx4 v[158:159], v[62:65], off
	s_waitcnt vmcnt(29)
	v_pk_add_f32 v[58:59], v[58:59], v[200:201]
	v_pk_add_f32 v[60:61], v[60:61], v[202:203]
	global_store_dwordx4 v[158:159], v[58:61], off offset:64
	s_waitcnt vmcnt(28)
	v_pk_add_f32 v[54:55], v[54:55], v[204:205]
	v_pk_add_f32 v[56:57], v[56:57], v[206:207]
	global_store_dwordx4 v[158:159], v[54:57], off offset:512
	s_waitcnt vmcnt(27)
	v_pk_add_f32 v[50:51], v[50:51], v[208:209]
	v_pk_add_f32 v[52:53], v[52:53], v[210:211]
	global_store_dwordx4 v[158:159], v[50:53], off offset:576
	s_mov_b64 s[2:3], 0x120000
	v_lshl_add_u64 v[158:159], v[154:155], 0, s[2:3]
	s_waitcnt vmcnt(26)
	v_pk_add_f32 v[46:47], v[46:47], v[212:213]
	v_pk_add_f32 v[48:49], v[48:49], v[214:215]
	global_store_dwordx4 v[158:159], v[46:49], off
	s_waitcnt vmcnt(25)
	v_pk_add_f32 v[42:43], v[42:43], v[216:217]
	v_pk_add_f32 v[44:45], v[44:45], v[218:219]
	global_store_dwordx4 v[158:159], v[42:45], off offset:64
	s_waitcnt vmcnt(24)
	v_pk_add_f32 v[38:39], v[38:39], v[220:221]
	v_pk_add_f32 v[40:41], v[40:41], v[222:223]
	global_store_dwordx4 v[158:159], v[38:41], off offset:512
	s_waitcnt vmcnt(23)
	v_pk_add_f32 v[34:35], v[34:35], v[224:225]
	v_pk_add_f32 v[36:37], v[36:37], v[226:227]
	global_store_dwordx4 v[158:159], v[34:37], off offset:576
	s_mov_b64 s[2:3], 0x140000
	v_lshl_add_u64 v[158:159], v[154:155], 0, s[2:3]
	s_waitcnt vmcnt(22)
	v_pk_add_f32 v[30:31], v[30:31], v[228:229]
	v_pk_add_f32 v[32:33], v[32:33], v[230:231]
	global_store_dwordx4 v[158:159], v[30:33], off
	s_waitcnt vmcnt(21)
	v_pk_add_f32 v[26:27], v[26:27], v[232:233]
	v_pk_add_f32 v[28:29], v[28:29], v[234:235]
	global_store_dwordx4 v[158:159], v[26:29], off offset:64
	s_waitcnt vmcnt(20)
	v_pk_add_f32 v[22:23], v[22:23], v[236:237]
	v_pk_add_f32 v[24:25], v[24:25], v[238:239]
	global_store_dwordx4 v[158:159], v[22:25], off offset:512
	s_waitcnt vmcnt(19)
	v_pk_add_f32 v[18:19], v[18:19], v[240:241]
	v_pk_add_f32 v[20:21], v[20:21], v[242:243]
	global_store_dwordx4 v[158:159], v[18:21], off offset:576
	s_mov_b64 s[2:3], 0x160000
	v_lshl_add_u64 v[158:159], v[154:155], 0, s[2:3]
	s_waitcnt vmcnt(18)
	v_pk_add_f32 v[14:15], v[14:15], v[244:245]
	v_pk_add_f32 v[16:17], v[16:17], v[246:247]
	global_store_dwordx4 v[158:159], v[14:17], off
	s_waitcnt vmcnt(17)
	v_pk_add_f32 v[10:11], v[10:11], v[248:249]
	v_pk_add_f32 v[12:13], v[12:13], v[250:251]
	global_store_dwordx4 v[158:159], v[10:13], off offset:64
	s_waitcnt vmcnt(16)
	v_pk_add_f32 v[6:7], v[6:7], v[146:147]
	v_pk_add_f32 v[8:9], v[8:9], v[148:149]
	global_store_dwordx4 v[158:159], v[6:9], off offset:512
	s_waitcnt vmcnt(15)
	v_pk_add_f32 v[2:3], v[2:3], v[150:151]
	v_pk_add_f32 v[4:5], v[4:5], v[152:153]
	global_store_dwordx4 v[158:159], v[2:5], off offset:576
	s_mov_b64 s[2:3], -1
	s_andn2_b64 vcc, exec, s[8:9]
	s_cbranch_vccnz .LBB0_510
	s_andn2_b64 vcc, exec, s[4:5]
	s_cbranch_vccnz .LBB0_509
	s_barrier
	s_branch .LBB0_509
